# speedup vs baseline: 1.0076x; 1.0047x over previous
; __device__ __forceinline__ float fexp2(float x) { return __builtin_amdgcn_exp2f(x); }
; __device__ __forceinline__ float flog2(float x) { return __builtin_amdgcn_logf(x); }
; template <int MODE>
; __device__ __forceinline__ void sb_step(const char* Kb, const char* Vb, const bf16x8 (&qf)[2][2], const SbConst& U,
;                                         f32x4 (&oacc)[4][2], float (&carry)[2], int key0, int q0, int fr, int fq) {
;     ...
;   for (int ks = 0; ks < 2; ++ks)
; #pragma unroll
;     for (int m = 0; m < 4; ++m) {
;       if (SB_CLS(m, 0) > 0 && SB_CLS(m, 1) > 0) continue;
;       const bf16x8 kf = *(const bf16x8*)(Kb + (m * 16 + fr) * 144 + ks * 64 + fq * 16);
; #pragma unroll
;       for (int n = 0; n < 2; ++n)
;         if (SB_CLS(m, n) <= 0) s[m][n] = mfma16(kf, qf[n][ks], s[m][n]);
;     }
; #pragma unroll
;   for (int n = 0; n < 2; ++n) {
;     unsigned pk[8];
;     const int tq = q0 + n * 16 + fr;
; #pragma unroll
;     for (int m = 0; m < 4; ++m) {
;       if (SB_CLS(m, n) > 0) { pk[m * 2] = 0u; pk[m * 2 + 1] = 0u; continue; }
;       float spv[4];
; #pragma unroll
;       for (int r = 0; r < 4; ++r) {
;         const float z = fminf(s[m][n][r], 80.f);
;         const float e = fexp2(z);
;         float sp = flog2(1.0f + e);
;         float ls = z - sp;
;         if (SB_CLS(m, n) == 0) {
;           const int key = key0 + m * 16 + fq * 4 + r;
;           if (key >= tq) { sp = 0.f; ls = -1e30f; }
;         }
;         spv[r] = sp;
;         s[m][n][r] = ls;
;       }
;       pk[m * 2] = pack2(spv[0], spv[1]);
;       pk[m * 2 + 1] = pack2(spv[2], spv[3]);
;     }
;     const bf16x8 sp0 = mk8(pk[0], pk[1], pk[2], pk[3]);
;     const bf16x8 sp1 = mk8(pk[4], pk[5], pk[6], pk[7]);
;     const float c = carry[n];
;     const f32x4 cin = {c, c, c, c};
;     const f32x4 X1 = mfma16(U.U_ONES, sp1, cin);
;     const f32x4 I0 = mfma16(U.U_TRI1, sp0, X1);
;     const f32x4 I1 = mfma16(U.U_0TRI, sp0, X1);
;     const f32x4 TOT = mfma16(U.U_ONES, sp0, X1);
;     const f32x4 I2 = mfma16(U.U_TRI1, sp1, cin);
;     const f32x4 I3 = mfma16(U.U_0TRI, sp1, cin);
.LBB0_393:
	v_cmp_le_i32_e64 s[10:11], s25, v156
	s_xor_b64 s[12:13], s[70:71], -1
	s_and_b64 s[10:11], s[10:11], s[12:13]
	s_andn2_b64 s[12:13], s[70:71], exec
	s_and_b64 s[14:15], s[70:71], exec
	s_or_b64 s[70:71], s[12:13], s[14:15]
	s_and_saveexec_b64 s[74:75], s[10:11]
	s_cbranch_execz .LBB0_392
	v_cmp_ne_u32_e64 s[10:11], s94, v192
	s_and_saveexec_b64 s[12:13], s[10:11]
	s_xor_b64 s[54:55], exec, s[12:13]
	s_cbranch_execz .LBB0_400
	s_waitcnt lgkmcnt(3)
	ds_read_b128 v[136:139], v159
	s_waitcnt lgkmcnt(3)
	ds_read_b128 v[132:135], v159 offset:2304
	s_waitcnt lgkmcnt(3)
	ds_read_b128 v[128:131], v159 offset:4608
	s_waitcnt lgkmcnt(3)
	ds_read_b128 v[124:127], v159 offset:6912
	v_cmp_ne_u32_e64 s[10:11], s94, v191
	s_and_saveexec_b64 s[12:13], s[10:11]
	s_xor_b64 s[10:11], exec, s[12:13]
	s_cbranch_execz .LBB0_397
	ds_read_b128 v[180:183], v159 offset:64
	s_waitcnt lgkmcnt(4)
	v_mfma_f32_16x16x32_bf16 v[140:143], v[136:139], v[68:71], 0
	s_mov_b32 s58, s56
	s_mov_b32 s59, s56
	s_mov_b32 s57, s56
	v_mfma_f32_16x16x32_bf16 v[136:139], v[136:139], v[76:79], 0
	s_waitcnt lgkmcnt(0)
	v_mfma_f32_16x16x32_bf16 v[194:197], v[180:183], v[72:75], v[140:143]
	s_nop 2
	ds_read_b128 v[140:143], v159 offset:2368
	v_mfma_f32_16x16x32_bf16 v[144:147], v[132:135], v[68:71], 0
	s_nop 2
	v_min_f32_e32 v86, 0x42a00000, v196
	v_exp_f32_e32 v87, v86
	v_mfma_f32_16x16x32_bf16 v[132:135], v[132:135], v[76:79], 0
	v_add_f32_e32 v87, 1.0, v87
	v_log_f32_e32 v87, v87
	v_mfma_f32_16x16x32_bf16 v[136:139], v[180:183], v[80:83], v[136:139]
	v_min_f32_e32 v0, 0x42a00000, v194
	v_min_f32_e32 v3, 0x42a00000, v195
	v_sub_f32_e32 v97, v86, v87
	v_min_f32_e32 v86, 0x42a00000, v197
	v_exp_f32_e32 v98, v86
	s_waitcnt lgkmcnt(0)
	v_mfma_f32_16x16x32_bf16 v[180:183], v[140:143], v[72:75], v[144:147]
	v_exp_f32_e32 v1, v0
	v_exp_f32_e32 v85, v3
	v_add_f32_e32 v98, 1.0, v98
	v_mfma_f32_16x16x32_bf16 v[132:135], v[140:143], v[80:83], v[132:135]
	ds_read_b128 v[140:143], v159 offset:4672
	ds_read_b128 v[144:147], v159 offset:6976
	v_log_f32_e32 v98, v98
	v_mfma_f32_16x16x32_bf16 v[148:151], v[128:131], v[68:71], 0
	v_add_f32_e32 v1, 1.0, v1
	v_add_f32_e32 v85, 1.0, v85
	v_sub_f32_e32 v99, v86, v98
	v_mfma_f32_16x16x32_bf16 v[128:131], v[128:131], v[76:79], 0
	v_min_f32_e32 v86, 0x42a00000, v181
	v_log_f32_e32 v1, v1
	v_mfma_f32_16x16x32_bf16 v[152:155], v[124:127], v[68:71], 0
	v_log_f32_e32 v85, v85
	v_sub_f32_e32 v0, v0, v1
	v_mfma_f32_16x16x32_bf16 v[124:127], v[124:127], v[76:79], 0
	v_sub_f32_e32 v3, v3, v85
	s_waitcnt lgkmcnt(1)
	v_mfma_f32_16x16x32_bf16 v[148:151], v[140:143], v[72:75], v[148:151]
	v_mfma_f32_16x16x32_bf16 v[128:131], v[140:143], v[80:83], v[128:131]
	s_waitcnt lgkmcnt(0)
	v_mfma_f32_16x16x32_bf16 v[140:143], v[144:147], v[72:75], v[152:155]
	v_mfma_f32_16x16x32_bf16 v[124:127], v[144:147], v[80:83], v[124:127]
	v_cvt_pk_bf16_f32 v144, v1, v85
	v_min_f32_e32 v250, 0x42a00000, v182
	v_min_f32_e32 v1, 0x42a00000, v180
	v_exp_f32_e32 v251, v250
	v_exp_f32_e32 v248, v86
	v_exp_f32_e32 v249, v1
	v_add_f32_e32 v251, 1.0, v251
	v_add_f32_e32 v248, 1.0, v248
	v_add_f32_e32 v249, 1.0, v249
	v_log_f32_e32 v147, v251
	v_log_f32_e32 v248, v248
	v_log_f32_e32 v249, v249
	v_cvt_pk_bf16_f32 v145, v87, v98
	v_sub_f32_e32 v193, v250, v147
	v_sub_f32_e32 v98, v86, v248
	v_cvt_pk_bf16_f32 v146, v249, v248
	v_min_f32_e32 v250, 0x42a00000, v148
	v_sub_f32_e32 v1, v1, v249
	v_min_f32_e32 v252, 0x42a00000, v183
	v_exp_f32_e32 v251, v250
	v_min_f32_e32 v248, 0x42a00000, v149
	v_exp_f32_e32 v253, v252
	v_exp_f32_e32 v249, v248
	v_add_f32_e32 v251, 1.0, v251
	v_add_f32_e32 v253, 1.0, v253
	v_log_f32_e32 v251, v251
	v_add_f32_e32 v249, 1.0, v249
	v_log_f32_e32 v152, v253
	v_log_f32_e32 v249, v249
	v_sub_f32_e32 v203, v250, v251
	v_sub_f32_e32 v202, v252, v152
	v_sub_f32_e32 v204, v248, v249
	v_min_f32_e32 v253, 0x42a00000, v150
	v_min_f32_e32 v250, 0x42a00000, v151
	v_exp_f32_e32 v252, v253
	v_exp_f32_e32 v248, v250
	v_add_f32_e32 v252, 1.0, v252
	v_add_f32_e32 v248, 1.0, v248
	v_log_f32_e32 v149, v252
	v_log_f32_e32 v150, v248
	v_sub_f32_e32 v205, v253, v149
	v_cvt_pk_bf16_f32 v148, v251, v249
	v_sub_f32_e32 v206, v250, v150
	v_min_f32_e32 v253, 0x42a00000, v140
	v_min_f32_e32 v251, 0x42a00000, v141
	v_min_f32_e32 v250, 0x42a00000, v142
	v_min_f32_e32 v85, 0x42a00000, v143
	v_exp_f32_e32 v252, v253
	v_exp_f32_e32 v249, v251
	v_exp_f32_e32 v140, v250
	v_exp_f32_e32 v141, v85
	v_add_f32_e32 v252, 1.0, v252
	v_add_f32_e32 v249, 1.0, v249
	v_add_f32_e32 v140, 1.0, v140
	v_add_f32_e32 v141, 1.0, v141
	v_log_f32_e32 v252, v252
	v_log_f32_e32 v249, v249
	v_log_f32_e32 v140, v140
	v_log_f32_e32 v141, v141
	v_cvt_pk_bf16_f32 v149, v149, v150
	v_cvt_pk_bf16_f32 v147, v147, v152
	v_sub_f32_e32 v207, v253, v252
	v_sub_f32_e32 v208, v251, v249
	v_cvt_pk_bf16_f32 v150, v252, v249
	v_mov_b32_e32 v86, v84
	v_mov_b32_e32 v87, v84
	v_sub_f32_e32 v209, v250, v140
	v_sub_f32_e32 v210, v85, v141
	v_cvt_pk_bf16_f32 v151, v140, v141
	v_mov_b64_e32 v[142:143], s[58:59]
	v_mov_b64_e32 v[140:141], s[56:57]
	v_mov_b32_e32 v85, v84
	s_nop 1
	v_mfma_f32_16x16x32_bf16 v[180:183], v[140:143], v[148:151], v[84:87]
	v_mfma_f32_16x16x32_bf16 v[152:155], v[4:7], v[144:147], v[180:183]
	v_mfma_f32_16x16x32_bf16 v[194:197], v[64:67], v[144:147], v[180:183]
	v_mfma_f32_16x16x32_bf16 v[198:201], v[4:7], v[148:151], v[84:87]
	s_nop 5
	v_sub_f32_e32 v0, v0, v152
	v_exp_f32_e32 v211, v0
	v_sub_f32_e32 v0, v1, v194
	v_mfma_f32_16x16x32_bf16 v[84:87], v[64:67], v[148:151], v[84:87]
	v_sub_f32_e32 v3, v3, v153
	v_exp_f32_e32 v153, v3
	v_sub_f32_e32 v3, v98, v195
	v_max_f32_e32 v98, v138, v138
	v_min_f32_e32 v98, 0x42a00000, v98
; __device__ __forceinline__ float fexp2(float x) { return __builtin_amdgcn_exp2f(x); }
; __device__ __forceinline__ float flog2(float x) { return __builtin_amdgcn_logf(x); }
; template <int MODE>
; __device__ __forceinline__ void sb_step(const char* Kb, const char* Vb, const bf16x8 (&qf)[2][2], const SbConst& U,
;                                         f32x4 (&oacc)[4][2], float (&carry)[2], int key0, int q0, int fr, int fq) {
;     ...
;     for (int m = 0; m < 4; ++m) {
;       if (SB_CLS(m, n) > 0) { pk[m * 2] = 0u; pk[m * 2 + 1] = 0u; continue; }
;       float spv[4];
; #pragma unroll
;       for (int r = 0; r < 4; ++r) {
;         const float z = fminf(s[m][n][r], 80.f);
;         const float e = fexp2(z);
;         float sp = flog2(1.0f + e);
;         float ls = z - sp;
;         if (SB_CLS(m, n) == 0) {
;           const int key = key0 + m * 16 + fq * 4 + r;
;           if (key >= tq) { sp = 0.f; ls = -1e30f; }
;         }
;         spv[r] = sp;
;         s[m][n][r] = ls;
;       }
;       pk[m * 2] = pack2(spv[0], spv[1]);
;       pk[m * 2 + 1] = pack2(spv[2], spv[3]);
;     }
;     const bf16x8 sp0 = mk8(pk[0], pk[1], pk[2], pk[3]);
;     const bf16x8 sp1 = mk8(pk[4], pk[5], pk[6], pk[7]);
;     const float c = carry[n];
;     const f32x4 cin = {c, c, c, c};
;     const f32x4 X1 = mfma16(U.U_ONES, sp1, cin);
;     const f32x4 I0 = mfma16(U.U_TRI1, sp0, X1);
;     const f32x4 I1 = mfma16(U.U_0TRI, sp0, X1);
;     const f32x4 TOT = mfma16(U.U_ONES, sp0, X1);
;     const f32x4 I2 = mfma16(U.U_TRI1, sp1, cin);
;     const f32x4 I3 = mfma16(U.U_0TRI, sp1, cin);
; #pragma unroll
;     for (int r = 0; r < 4; ++r) {
;       s[0][n][r] = (SB_CLS(0, n) > 0) ? 0.f : fexp2(s[0][n][r] - I0[r]);
;       s[1][n][r] = (SB_CLS(1, n) > 0) ? 0.f : fexp2(s[1][n][r] - I1[r]);
;       s[2][n][r] = (SB_CLS(2, n) > 0) ? 0.f : fexp2(s[2][n][r] - I2[r]);
;       s[3][n][r] = (SB_CLS(3, n) > 0) ? 0.f : fexp2(s[3][n][r] - I3[r]);
;     }
	s_nop 2
	v_sub_f32_e32 v1, v207, v84
	v_sub_f32_e32 v84, v208, v85
	v_exp_f32_e32 v148, v84
	v_sub_f32_e32 v84, v97, v154
	v_exp_f32_e32 v154, v84
	v_sub_f32_e32 v84, v193, v196
	v_exp_f32_e32 v193, v84
	v_sub_f32_e32 v84, v205, v200
	v_exp_f32_e32 v149, v84
	v_sub_f32_e32 v84, v209, v86
	v_exp_f32_e32 v150, v84
	v_sub_f32_e32 v84, v99, v155
	v_exp_f32_e32 v99, v98
	v_exp_f32_e32 v155, v84
	v_sub_f32_e32 v84, v202, v197
	v_exp_f32_e32 v196, v84
	v_add_f32_e32 v99, 1.0, v99
	v_log_f32_e32 v99, v99
	v_sub_f32_e32 v84, v206, v201
	v_exp_f32_e32 v151, v84
	v_sub_f32_e32 v84, v210, v87
	v_sub_f32_e32 v197, v98, v99
	v_exp_f32_e32 v152, v84
	v_mfma_f32_16x16x32_bf16 v[84:87], v[140:143], v[144:147], v[180:183]
	v_min_f32_e32 v98, 0x42a00000, v139
	v_exp_f32_e32 v194, v0
	v_sub_f32_e32 v0, v203, v198
	v_exp_f32_e32 v195, v3
	v_sub_f32_e32 v3, v204, v199
	s_nop 2
	v_max_f32_e32 v85, v136, v136
	v_exp_f32_e32 v248, v98
	v_min_f32_e32 v85, 0x42a00000, v85
	v_min_f32_e32 v87, 0x42a00000, v137
	v_add_f32_e32 v248, 1.0, v248
	v_exp_f32_e32 v249, v85
	v_exp_f32_e32 v250, v87
	v_min_f32_e32 v251, 0x42a00000, v133
	v_min_f32_e32 v253, 0x42a00000, v134
	v_max_f32_e32 v86, v132, v132
	v_log_f32_e32 v137, v248
	v_exp_f32_e32 v252, v251
	v_exp_f32_e32 v132, v253
	v_min_f32_e32 v86, 0x42a00000, v86
	v_add_f32_e32 v249, 1.0, v249
	v_add_f32_e32 v250, 1.0, v250
	v_exp_f32_e32 v248, v86
	v_log_f32_e32 v249, v249
	v_add_f32_e32 v252, 1.0, v252
	v_log_f32_e32 v250, v250
	v_add_f32_e32 v132, 1.0, v132
	v_log_f32_e32 v252, v252
	v_log_f32_e32 v132, v132
	v_add_f32_e32 v248, 1.0, v248
	v_sub_f32_e32 v85, v85, v249
	v_cvt_pk_bf16_f32 v136, v249, v250
	v_log_f32_e32 v248, v248
	v_sub_f32_e32 v199, v251, v252
	v_sub_f32_e32 v87, v87, v250
	v_sub_f32_e32 v200, v253, v132
	v_min_f32_e32 v249, 0x42a00000, v128
	v_min_f32_e32 v251, 0x42a00000, v135
	v_cvt_pk_bf16_f32 v138, v248, v252
	v_exp_f32_e32 v250, v249
	v_min_f32_e32 v253, 0x42a00000, v129
	v_exp_f32_e32 v133, v251
	v_exp_f32_e32 v252, v253
	v_add_f32_e32 v250, 1.0, v250
	v_add_f32_e32 v133, 1.0, v133
	v_log_f32_e32 v250, v250
	v_add_f32_e32 v252, 1.0, v252
	v_log_f32_e32 v133, v133
	v_log_f32_e32 v252, v252
	v_sub_f32_e32 v86, v86, v248
	v_sub_f32_e32 v202, v249, v250
	v_sub_f32_e32 v201, v251, v133
	v_sub_f32_e32 v203, v253, v252
	v_min_f32_e32 v248, 0x42a00000, v130
	v_min_f32_e32 v249, 0x42a00000, v131
	v_exp_f32_e32 v251, v248
	v_exp_f32_e32 v253, v249
	v_add_f32_e32 v251, 1.0, v251
	v_add_f32_e32 v253, 1.0, v253
	v_log_f32_e32 v129, v251
	v_log_f32_e32 v130, v253
	v_sub_f32_e32 v204, v248, v129
	v_cvt_pk_bf16_f32 v128, v250, v252
	v_sub_f32_e32 v205, v249, v130
	v_min_f32_e32 v248, 0x42a00000, v124
	v_min_f32_e32 v250, 0x42a00000, v125
	v_min_f32_e32 v249, 0x42a00000, v126
	v_min_f32_e32 v253, 0x42a00000, v127
	v_exp_f32_e32 v251, v248
	v_exp_f32_e32 v252, v250
	v_exp_f32_e32 v124, v249
	v_exp_f32_e32 v125, v253
	v_add_f32_e32 v251, 1.0, v251
	v_add_f32_e32 v252, 1.0, v252
	v_add_f32_e32 v124, 1.0, v124
	v_add_f32_e32 v125, 1.0, v125
	v_sub_f32_e32 v198, v98, v137
	v_log_f32_e32 v251, v251
	v_log_f32_e32 v252, v252
	v_log_f32_e32 v124, v124
	v_log_f32_e32 v125, v125
	v_cvt_pk_bf16_f32 v137, v99, v137
	v_cvt_pk_bf16_f32 v129, v129, v130
	v_exp_f32_e32 v0, v0
	v_exp_f32_e32 v1, v1
	v_exp_f32_e32 v3, v3
	v_cvt_pk_bf16_f32 v139, v132, v133
	v_sub_f32_e32 v206, v248, v251
	v_sub_f32_e32 v207, v250, v252
	v_cvt_pk_bf16_f32 v130, v251, v252
	v_mov_b32_e32 v98, v96
	v_mov_b32_e32 v99, v96
	v_sub_f32_e32 v208, v249, v124
	v_sub_f32_e32 v209, v253, v125
	v_cvt_pk_bf16_f32 v131, v124, v125
	v_mov_b32_e32 v97, v96
	s_nop 1
	v_mfma_f32_16x16x32_bf16 v[124:127], v[140:143], v[128:131], v[96:99]
	v_mfma_f32_16x16x32_bf16 v[180:183], v[4:7], v[128:131], v[96:99]
	v_mfma_f32_16x16x32_bf16 v[96:99], v[64:67], v[128:131], v[96:99]
	v_mfma_f32_16x16x32_bf16 v[144:147], v[64:67], v[136:139], v[124:127]
	s_nop 5
	v_sub_f32_e32 v128, v202, v180
	v_sub_f32_e32 v96, v206, v96
	v_exp_f32_e32 v180, v96
	v_mfma_f32_16x16x32_bf16 v[132:135], v[4:7], v[136:139], v[124:127]
	v_sub_f32_e32 v96, v199, v145
	v_exp_f32_e32 v130, v96
	v_sub_f32_e32 v96, v203, v181
	v_exp_f32_e32 v145, v96
	v_sub_f32_e32 v96, v207, v97
	v_exp_f32_e32 v181, v96
	s_nop 1
	v_sub_f32_e32 v96, v197, v134
	v_exp_f32_e32 v129, v96
	v_sub_f32_e32 v96, v200, v146
	v_exp_f32_e32 v131, v96
	v_sub_f32_e32 v96, v204, v182
	v_exp_f32_e32 v146, v96
	v_sub_f32_e32 v96, v208, v98
	v_exp_f32_e32 v182, v96
	v_sub_f32_e32 v96, v198, v135
	v_sub_f32_e32 v85, v85, v132
	v_exp_f32_e32 v132, v96
	v_sub_f32_e32 v96, v201, v147
	v_sub_f32_e32 v87, v87, v133
	v_exp_f32_e32 v133, v96
	v_cvt_pk_bf16_f32 v129, v129, v132
	v_sub_f32_e32 v86, v86, v144
	v_exp_f32_e32 v85, v85
	v_cvt_pk_bf16_f32 v131, v131, v133
	ds_read2_b64 v[132:135], v177 offset1:4
	v_exp_f32_e32 v86, v86
	v_exp_f32_e32 v87, v87
	v_sub_f32_e32 v96, v205, v183
	v_exp_f32_e32 v147, v96
	v_sub_f32_e32 v96, v209, v99
	v_exp_f32_e32 v144, v128
	v_exp_f32_e32 v183, v96
	v_mfma_f32_16x16x32_bf16 v[96:99], v[140:143], v[136:139], v[124:127]
	v_cvt_pk_bf16_f32 v128, v85, v87
	v_cvt_pk_bf16_f32 v130, v86, v130
	v_add_u32_e32 v85, 0x800, v177
	v_cvt_pk_bf16_f32 v124, v211, v153
	v_cvt_pk_bf16_f32 v125, v154, v155
	v_cvt_pk_bf16_f32 v126, v194, v195
	v_cvt_pk_bf16_f32 v127, v193, v196
	s_waitcnt lgkmcnt(0)
; template <int MODE>
; __device__ __forceinline__ void sb_step(const char* Kb, const char* Vb, const bf16x8 (&qf)[2][2], const SbConst& U,
;                                         f32x4 (&oacc)[4][2], float (&carry)[2], int key0, int q0, int fr, int fq) {
;     ...
; #pragma unroll
;   for (int ks = 0; ks < 2; ++ks) {
;     bf16x8 pf[2];
; #pragma unroll
;     for (int n = 0; n < 2; ++n)
;       pf[n] = mk8(pack2(s[2 * ks][n][0], s[2 * ks][n][1]), pack2(s[2 * ks][n][2], s[2 * ks][n][3]),
;                   pack2(s[2 * ks + 1][n][0], s[2 * ks + 1][n][1]), pack2(s[2 * ks + 1][n][2], s[2 * ks + 1][n][3]));
; #pragma unroll
;     for (int mt = 0; mt < 4; ++mt) {
;       const char* vp = Vb + (mt * 16 + fr) * 144 + (32 * ks + 4 * fq) * 2;
;       const u32x2 lo = *(const u32x2*)vp;
;       const u32x2 hi = *(const u32x2*)(vp + 32);
;       const bf16x8 vf = mk8(lo[0], lo[1], hi[0], hi[1]);
; #pragma unroll
;       for (int n = 0; n < 2; ++n) oacc[mt][n] = mfma16(vf, pf[n], oacc[mt][n]);
;     }
;   }
	v_mfma_f32_16x16x32_bf16 v[116:119], v[132:135], v[128:131], v[116:119]
	v_add_u32_e32 v97, 0x1000, v177
	v_add_u32_e32 v136, 0x1800, v177
	v_mfma_f32_16x16x32_bf16 v[120:123], v[132:135], v[124:127], v[120:123]
	ds_read2_b64 v[132:135], v85 offset0:32 offset1:36
	s_waitcnt lgkmcnt(0)
	v_mfma_f32_16x16x32_bf16 v[112:115], v[132:135], v[124:127], v[112:115]
	v_mfma_f32_16x16x32_bf16 v[108:111], v[132:135], v[128:131], v[108:111]
	ds_read2_b64 v[132:135], v97 offset0:64 offset1:68
	s_waitcnt lgkmcnt(0)
	v_mfma_f32_16x16x32_bf16 v[104:107], v[132:135], v[124:127], v[104:107]
	v_mfma_f32_16x16x32_bf16 v[98:101], v[132:135], v[128:131], v[100:103]
	ds_read2_b64 v[132:135], v136 offset0:96 offset1:100
	s_waitcnt lgkmcnt(0)
	v_mfma_f32_16x16x32_bf16 v[92:95], v[132:135], v[124:127], v[92:95]
	v_cvt_pk_bf16_f32 v124, v0, v3
	v_cvt_pk_bf16_f32 v125, v149, v151
	v_cvt_pk_bf16_f32 v126, v1, v148
	v_mfma_f32_16x16x32_bf16 v[86:89], v[132:135], v[128:131], v[88:91]
	ds_read2_b64 v[132:135], v177 offset0:8 offset1:12
	v_cvt_pk_bf16_f32 v127, v150, v152
	v_cvt_pk_bf16_f32 v128, v144, v145
	v_cvt_pk_bf16_f32 v129, v146, v147
	v_cvt_pk_bf16_f32 v130, v180, v181
	v_cvt_pk_bf16_f32 v131, v182, v183
	s_waitcnt lgkmcnt(0)
	v_mfma_f32_16x16x32_bf16 v[120:123], v[132:135], v[124:127], v[120:123]
	v_mfma_f32_16x16x32_bf16 v[116:119], v[132:135], v[128:131], v[116:119]
	ds_read2_b64 v[132:135], v85 offset0:40 offset1:44
	s_waitcnt lgkmcnt(0)
	v_mfma_f32_16x16x32_bf16 v[112:115], v[132:135], v[124:127], v[112:115]
	v_mfma_f32_16x16x32_bf16 v[108:111], v[132:135], v[128:131], v[108:111]
	ds_read2_b64 v[132:135], v97 offset0:72 offset1:76
	s_waitcnt lgkmcnt(0)
	v_mfma_f32_16x16x32_bf16 v[104:107], v[132:135], v[124:127], v[104:107]
	v_mfma_f32_16x16x32_bf16 v[100:103], v[132:135], v[128:131], v[98:101]
	ds_read2_b64 v[132:135], v136 offset0:104 offset1:108
	s_waitcnt lgkmcnt(0)
	v_mfma_f32_16x16x32_bf16 v[92:95], v[132:135], v[124:127], v[92:95]
	v_mfma_f32_16x16x32_bf16 v[88:91], v[132:135], v[128:131], v[86:89]
